# removed the remaining compiler-inserted s_waitcnt vmcnt(0) at the end of the GEMM job prologues (EP_SCALE, EP_SILU, EP_U): only LDS-DMA stages are outstanding there and the K-loop's counted waits cove
# speedup vs baseline: 1.0023x; 1.0002x over previous
.LBB0_335:
	s_add_i32 m0, s22, 0x18000
	v_lshl_add_u64 v[0:1], v[0:1], 0, s[96:97]
	s_waitcnt vmcnt(4)
	s_barrier
	global_load_lds_dwordx4 v[0:1], off
	v_lshl_add_u64 v[0:1], v[2:3], 0, s[96:97]
	s_add_i32 m0, s22, 0x1a000
	s_add_i32 s28, s22, 0x8000
	global_load_lds_dwordx4 v[0:1], off
	v_lshl_add_u64 v[0:1], v[4:5], 0, s[96:97]
	s_mov_b32 m0, s28
	s_add_i32 s29, s22, 0xa000
	global_load_lds_dwordx4 v[0:1], off
	v_lshl_add_u64 v[0:1], v[6:7], 0, s[96:97]
	s_mov_b32 m0, s29
	v_lshl_or_b32 v150, s6, 6, v217
	global_load_lds_dwordx4 v[0:1], off
	s_add_i32 m0, s22, 0x1c000
	v_lshl_add_u64 v[0:1], v[8:9], 0, s[96:97]
	global_load_lds_dwordx4 v[0:1], off
	v_lshl_add_u64 v[0:1], v[10:11], 0, s[96:97]
	s_add_i32 m0, s22, 0x1e000
	v_lshl_or_b32 v12, v217, 6, v226
	global_load_lds_dwordx4 v[0:1], off
	s_lshl_b32 s6, s6, 13
	v_bitop3_b32 v12, v12, s6, v227 bitop3:0xde
	s_lshl_b32 s6, s3, 5
	s_and_b32 s10, s6, 0x60
	s_add_i32 s6, 0, 0x20040
	s_add_i32 s46, s6, s17
	v_lshl_add_u32 v152, v150, 3, s6
	s_lshl_b32 s6, s3, 7
	s_ashr_i32 s7, s6, 31
	s_add_i32 s48, s41, -2
	s_lshl_b64 s[6:7], s[6:7], 3
	v_readlane_b32 s8, v254, 25
	v_readlane_b32 s9, v254, 26
	s_add_u32 s6, s8, s6
	s_addc_u32 s7, s9, s7
	v_lshlrev_b32_e32 v0, 3, v164
	v_mov_b32_e32 v1, v161
	v_lshl_add_u64 v[142:143], s[6:7], 0, v[0:1]
	v_readlane_b32 s6, v254, 29
	v_readlane_b32 s7, v254, 30
	s_ashr_i32 s7, s6, 31
	s_lshr_b32 s3, s7, 29
	s_add_i32 s3, s6, s3
	s_ashr_i32 s57, s3, 3
	s_and_b32 s3, s3, -8
	s_ashr_i32 s49, s47, 31
	v_writelane_b32 v254, s6, 29
	s_sub_i32 s88, s6, s3
	s_add_i32 s89, s57, 1
	s_lshl_b32 s90, s92, 3
	s_cmp_lg_u32 s75, 0
	s_cselect_b64 s[58:59], -1, 0
	s_mov_b32 s3, s92
	s_add_i32 s92, s75, -1
	v_writelane_b32 v254, s7, 30
	s_lshl_b64 s[6:7], s[92:93], 21
	s_cmp_eq_u32 s75, 0
	v_writelane_b32 v255, s6, 12
	s_cselect_b64 s[8:9], -1, 0
	s_waitcnt vmcnt(6)
	s_mov_b32 s37, 0
	v_writelane_b32 v255, s7, 13
	s_and_b64 s[6:7], s[8:9], exec
	v_readlane_b32 s6, v254, 14
	s_cselect_b32 s25, 0, 0
	v_readlane_b32 s7, v254, 15
	s_cselect_b32 s24, 0x500, s6
	v_writelane_b32 v255, s24, 14
	v_readlane_b32 s6, v254, 49
	v_readlane_b32 s7, v254, 50
	v_writelane_b32 v255, s25, 15
	v_writelane_b32 v255, s8, 16
	s_and_b64 s[60:61], s[6:7], s[8:9]
	v_readlane_b32 s24, v254, 27
	s_cmp_lg_u32 s75, 1
	v_readlane_b32 s25, v254, 28
	v_writelane_b32 v255, s9, 17
	s_cselect_b64 s[6:7], -1, 0
	s_xor_b64 s[8:9], s[24:25], -1
	s_or_b64 s[62:63], s[8:9], s[6:7]
	s_cmp_eq_u32 s75, 2
	s_cselect_b64 s[6:7], -1, 0
	s_and_b64 s[6:7], s[24:25], s[6:7]
	s_mov_b64 s[50:51], s[6:7]
	s_and_b64 s[6:7], s[6:7], exec
	s_cselect_b32 s36, 0x4000, 0
	s_abs_i32 s92, s90
	v_cvt_f32_u32_e32 v0, s92
	v_writelane_b32 v255, s3, 18
	s_bfe_i32 s55, s3, 0x1001c
	s_sub_i32 s3, 0, s92
	v_rcp_iflag_f32_e32 v0, v0
	v_lshl_or_b32 v151, s10, 7, v228
	s_mov_b32 s31, s75
	v_or_b32_e32 v153, s10, v225
	v_mul_f32_e32 v0, 0x4f7ffffe, v0
	v_cvt_u32_f32_e32 v0, v0
	v_lshl_add_u64 v[144:145], s[64:65], 0, v[138:139]
	v_lshl_add_u64 v[146:147], s[64:65], 0, v[136:137]
	v_add_u32_e32 v154, 0, v12
	v_readfirstlane_b32 s6, v0
	s_mul_i32 s3, s3, s6
	s_mul_hi_u32 s3, s6, s3
	s_add_i32 s24, s6, s3
	s_mov_b32 s54, s37
	s_barrier
	s_branch .LBB0_337

.LBB0_347:
	s_add_u32 s38, s20, 0x100
	s_addc_u32 s39, s21, 0
	s_add_u32 vcc_lo, s84, 0x80
	v_mov_b64_e32 v[0:1], 0
	v_mov_b64_e32 v[2:3], 0
	v_mov_b64_e32 v[4:5], 0
	v_mov_b64_e32 v[6:7], 0
	v_mov_b64_e32 v[8:9], 0
	v_mov_b64_e32 v[10:11], 0
	v_mov_b64_e32 v[12:13], 0
	v_mov_b64_e32 v[14:15], 0
	v_mov_b64_e32 v[16:17], 0
	v_mov_b64_e32 v[18:19], 0
	v_mov_b64_e32 v[20:21], 0
	v_mov_b64_e32 v[22:23], 0
	v_mov_b64_e32 v[24:25], 0
	v_mov_b64_e32 v[26:27], 0
	v_mov_b64_e32 v[28:29], 0
	v_mov_b64_e32 v[30:31], 0
	v_mov_b64_e32 v[32:33], 0
	v_mov_b64_e32 v[34:35], 0
	v_mov_b64_e32 v[36:37], 0
	v_mov_b64_e32 v[38:39], 0
	v_mov_b64_e32 v[40:41], 0
	v_mov_b64_e32 v[42:43], 0
	v_mov_b64_e32 v[44:45], 0
	v_mov_b64_e32 v[46:47], 0
	v_mov_b64_e32 v[48:49], 0
	v_mov_b64_e32 v[50:51], 0
	v_mov_b64_e32 v[52:53], 0
	v_mov_b64_e32 v[54:55], 0
	v_mov_b64_e32 v[56:57], 0
	v_mov_b64_e32 v[58:59], 0
	v_mov_b64_e32 v[60:61], 0
	v_mov_b64_e32 v[62:63], 0
	v_mov_b64_e32 v[64:65], 0
	v_mov_b64_e32 v[66:67], 0
	v_mov_b64_e32 v[68:69], 0
	v_mov_b64_e32 v[70:71], 0
	v_mov_b64_e32 v[72:73], 0
	v_mov_b64_e32 v[74:75], 0
	v_mov_b64_e32 v[76:77], 0
	v_mov_b64_e32 v[78:79], 0
	v_mov_b64_e32 v[80:81], 0
	v_mov_b64_e32 v[82:83], 0
	v_mov_b64_e32 v[84:85], 0
	v_mov_b64_e32 v[86:87], 0
	v_mov_b64_e32 v[88:89], 0
	v_mov_b64_e32 v[90:91], 0
	v_mov_b64_e32 v[92:93], 0
	v_mov_b64_e32 v[94:95], 0
	v_mov_b64_e32 v[96:97], 0
	v_mov_b64_e32 v[98:99], 0
	v_mov_b64_e32 v[100:101], 0
	v_mov_b64_e32 v[102:103], 0
	v_mov_b64_e32 v[104:105], 0
	v_mov_b64_e32 v[106:107], 0
	v_mov_b64_e32 v[108:109], 0
	v_mov_b64_e32 v[110:111], 0
	v_mov_b64_e32 v[112:113], 0
	v_mov_b64_e32 v[114:115], 0
	v_mov_b64_e32 v[116:117], 0
	v_mov_b64_e32 v[118:119], 0
	v_mov_b64_e32 v[120:121], 0
	v_mov_b64_e32 v[122:123], 0
	v_mov_b64_e32 v[124:125], 0
	v_mov_b64_e32 v[126:127], 0
	s_addc_u32 vcc_hi, s85, 0
	s_mov_b32 s20, 0
	s_nop 0

.LBB0_603:
	s_add_i32 m0, s57, 0x18000
	v_lshl_add_u64 v[0:1], v[0:1], 0, s[96:97]
	s_waitcnt vmcnt(4)
	s_barrier
	global_load_lds_dwordx4 v[0:1], off
	v_lshl_add_u64 v[0:1], v[2:3], 0, s[96:97]
	s_add_i32 m0, s57, 0x1a000
	s_add_i32 s55, s57, 0x8000
	global_load_lds_dwordx4 v[0:1], off
	v_lshl_add_u64 v[0:1], v[4:5], 0, s[96:97]
	s_mov_b32 m0, s55
	s_add_i32 s84, s57, 0xa000
	global_load_lds_dwordx4 v[0:1], off
	v_lshl_add_u64 v[0:1], v[6:7], 0, s[96:97]
	s_mov_b32 m0, s84
	s_lshl_b32 s0, s0, 5
	global_load_lds_dwordx4 v[0:1], off
	s_add_i32 m0, s57, 0x1c000
	v_lshl_add_u64 v[0:1], v[8:9], 0, s[96:97]
	global_load_lds_dwordx4 v[0:1], off
	v_lshl_add_u64 v[0:1], v[10:11], 0, s[96:97]
	s_add_i32 m0, s57, 0x1e000
	v_lshl_or_b32 v142, s1, 6, v217
	global_load_lds_dwordx4 v[0:1], off
	s_lshl_b32 s10, s1, 13
	s_and_b32 s11, s0, 0x60
	v_readlane_b32 s0, v254, 29
	s_ashr_i32 s7, s0, 31
	s_mov_b32 s6, s0
	s_lshr_b32 s0, s7, 29
	s_add_i32 s0, s6, s0
	s_ashr_i32 s89, s0, 3
	s_and_b32 s0, s0, -8
	s_add_i32 s85, s41, -2
	s_ashr_i32 s88, s47, 31
	v_readlane_b32 s1, v254, 30
	v_writelane_b32 v254, s6, 29
	s_sub_i32 s94, s6, s0
	s_add_i32 s95, s89, 1
	s_lshl_b32 s46, s92, 3
	s_cmp_lg_u32 s75, 0
	s_cselect_b64 s[0:1], -1, 0
	s_mov_b32 s17, s92
	s_add_i32 s92, s75, -1
	s_lshl_b64 s[12:13], s[92:93], 21
	s_cmp_eq_u32 s75, 0
	s_cselect_b64 s[14:15], -1, 0
	v_writelane_b32 v254, s7, 30
	s_and_b64 s[6:7], s[14:15], exec
	v_readlane_b32 s6, v254, 14
	v_readlane_b32 s7, v254, 15
	s_cselect_b32 s50, 0x500, s6
	v_readlane_b32 s6, v254, 49
	v_readlane_b32 s7, v254, 50
	s_cselect_b32 s51, 0, 0
	s_and_b64 s[58:59], s[6:7], s[14:15]
	v_readlane_b32 s22, v254, 27
	s_cmp_lg_u32 s75, 1
	v_readlane_b32 s23, v254, 28
	s_cselect_b64 s[6:7], -1, 0
	s_xor_b64 s[8:9], s[22:23], -1
	s_or_b64 s[60:61], s[8:9], s[6:7]
	s_cmp_eq_u32 s75, 2
	s_cselect_b64 s[6:7], -1, 0
	s_and_b64 s[62:63], s[22:23], s[6:7]
	s_and_b64 s[6:7], s[62:63], exec
	s_cselect_b32 s52, 0x4000, 0
	s_abs_i32 s92, s46
	v_cvt_f32_u32_e32 v1, s92
	s_sub_i32 s6, 0, s92
	v_lshl_or_b32 v0, v217, 6, v226
	s_waitcnt vmcnt(6)
	v_rcp_iflag_f32_e32 v1, v1
	v_bitop3_b32 v0, v0, s10, v227 bitop3:0xde
	s_mov_b32 s53, 0
	s_mov_b32 s56, s75
	v_mul_f32_e32 v1, 0x4f7ffffe, v1
	v_cvt_u32_f32_e32 v1, v1
	v_lshl_or_b32 v143, s11, 7, v228
	v_or_b32_e32 v144, s11, v225
	s_mov_b32 s90, s17
	v_readfirstlane_b32 s7, v1
	s_mul_i32 s6, s6, s7
	s_mul_hi_u32 s6, s7, s6
	s_bfe_i32 s22, s17, 0x1001c
	s_add_i32 s23, s7, s6
	v_lshl_add_u64 v[134:135], s[64:65], 0, v[130:131]
	v_lshl_add_u64 v[136:137], s[64:65], 0, v[128:129]
	v_add_u32_e32 v145, 0, v0
	s_mov_b32 s48, s53
	s_barrier
	s_branch .LBB0_606

.LBB0_616:
	s_add_u32 s17, s20, 0x100
	s_addc_u32 s24, s21, 0
	s_add_u32 s30, s30, 0x80
	v_mov_b64_e32 v[0:1], 0
	v_mov_b64_e32 v[2:3], 0
	v_mov_b64_e32 v[4:5], 0
	v_mov_b64_e32 v[6:7], 0
	v_mov_b64_e32 v[8:9], 0
	v_mov_b64_e32 v[10:11], 0
	v_mov_b64_e32 v[12:13], 0
	v_mov_b64_e32 v[14:15], 0
	v_mov_b64_e32 v[16:17], 0
	v_mov_b64_e32 v[18:19], 0
	v_mov_b64_e32 v[20:21], 0
	v_mov_b64_e32 v[22:23], 0
	v_mov_b64_e32 v[24:25], 0
	v_mov_b64_e32 v[26:27], 0
	v_mov_b64_e32 v[28:29], 0
	v_mov_b64_e32 v[30:31], 0
	v_mov_b64_e32 v[32:33], 0
	v_mov_b64_e32 v[34:35], 0
	v_mov_b64_e32 v[36:37], 0
	v_mov_b64_e32 v[38:39], 0
	v_mov_b64_e32 v[40:41], 0
	v_mov_b64_e32 v[42:43], 0
	v_mov_b64_e32 v[44:45], 0
	v_mov_b64_e32 v[46:47], 0
	v_mov_b64_e32 v[48:49], 0
	v_mov_b64_e32 v[50:51], 0
	v_mov_b64_e32 v[52:53], 0
	v_mov_b64_e32 v[54:55], 0
	v_mov_b64_e32 v[56:57], 0
	v_mov_b64_e32 v[58:59], 0
	v_mov_b64_e32 v[60:61], 0
	v_mov_b64_e32 v[62:63], 0
	v_mov_b64_e32 v[64:65], 0
	v_mov_b64_e32 v[66:67], 0
	v_mov_b64_e32 v[68:69], 0
	v_mov_b64_e32 v[70:71], 0
	v_mov_b64_e32 v[72:73], 0
	v_mov_b64_e32 v[74:75], 0
	v_mov_b64_e32 v[76:77], 0
	v_mov_b64_e32 v[78:79], 0
	v_mov_b64_e32 v[80:81], 0
	v_mov_b64_e32 v[82:83], 0
	v_mov_b64_e32 v[84:85], 0
	v_mov_b64_e32 v[86:87], 0
	v_mov_b64_e32 v[88:89], 0
	v_mov_b64_e32 v[90:91], 0
	v_mov_b64_e32 v[92:93], 0
	v_mov_b64_e32 v[94:95], 0
	v_mov_b64_e32 v[96:97], 0
	v_mov_b64_e32 v[98:99], 0
	v_mov_b64_e32 v[100:101], 0
	v_mov_b64_e32 v[102:103], 0
	v_mov_b64_e32 v[104:105], 0
	v_mov_b64_e32 v[106:107], 0
	v_mov_b64_e32 v[108:109], 0
	v_mov_b64_e32 v[110:111], 0
	v_mov_b64_e32 v[112:113], 0
	v_mov_b64_e32 v[114:115], 0
	v_mov_b64_e32 v[116:117], 0
	v_mov_b64_e32 v[118:119], 0
	v_mov_b64_e32 v[120:121], 0
	v_mov_b64_e32 v[122:123], 0
	v_mov_b64_e32 v[124:125], 0
	v_mov_b64_e32 v[126:127], 0
	s_addc_u32 s31, s31, 0
	s_mov_b32 s20, 0
	s_nop 0

.LBB0_665:
	s_add_i32 m0, s23, 0x18000
	v_lshl_add_u64 v[2:3], v[2:3], 0, s[96:97]
	s_waitcnt vmcnt(4)
	s_barrier
	global_load_lds_dwordx4 v[2:3], off
	v_lshl_add_u64 v[2:3], v[4:5], 0, s[96:97]
	s_add_i32 m0, s23, 0x1a000
	s_add_i32 s44, s23, 0x8000
	global_load_lds_dwordx4 v[2:3], off
	v_lshl_add_u64 v[2:3], v[6:7], 0, s[96:97]
	s_mov_b32 m0, s44
	s_add_i32 s45, s23, 0xa000
	global_load_lds_dwordx4 v[2:3], off
	v_lshl_add_u64 v[2:3], v[8:9], 0, s[96:97]
	s_mov_b32 m0, s45
	v_lshl_or_b32 v158, s7, 6, v217
	global_load_lds_dwordx4 v[2:3], off
	s_add_i32 m0, s23, 0x1c000
	v_lshl_add_u64 v[2:3], v[10:11], 0, s[96:97]
	global_load_lds_dwordx4 v[2:3], off
	v_lshl_add_u64 v[2:3], v[12:13], 0, s[96:97]
	s_add_i32 m0, s23, 0x1e000
	v_lshl_or_b32 v1, v217, 6, v226
	global_load_lds_dwordx4 v[2:3], off
	s_lshl_b32 s7, s7, 13
	v_bitop3_b32 v14, v1, s7, v227 bitop3:0xde
	s_lshl_b32 s7, s6, 5
	s_and_b32 s10, s7, 0x60
	s_add_i32 s7, 0, 0x20040
	s_lshl_b32 s6, s6, 7
	s_add_i32 s46, s7, s22
	v_lshl_add_u32 v166, v158, 3, s7
	s_ashr_i32 s7, s6, 31
	s_add_i32 s48, s41, -2
	s_lshl_b64 s[6:7], s[6:7], 3
	v_readlane_b32 s8, v254, 25
	v_readlane_b32 s9, v254, 26
	s_add_u32 s6, s8, s6
	s_addc_u32 s7, s9, s7
	v_mov_b32_e32 v1, v161
	v_lshl_add_u64 v[150:151], s[6:7], 0, v[0:1]
	v_readlane_b32 s6, v254, 29
	s_ashr_i32 s9, s6, 31
	s_mov_b32 s8, s6
	s_lshr_b32 s6, s9, 29
	s_add_i32 s6, s8, s6
	s_ashr_i32 s57, s6, 3
	s_and_b32 s6, s6, -8
	s_ashr_i32 s49, s47, 31
	s_sub_i32 s84, s8, s6
	s_add_i32 s85, s57, 1
	s_lshl_b32 s88, s92, 3
	s_cmp_lg_u32 s75, 0
	v_readlane_b32 s7, v254, 30
	s_cselect_b64 s[14:15], -1, 0
	s_mov_b32 s11, s92
	s_add_i32 s92, s75, -1
	s_lshl_b64 s[6:7], s[92:93], 21
	s_cmp_eq_u32 s75, 0
	s_mov_b64 s[58:59], s[8:9]
	v_writelane_b32 v254, s6, 29
	s_cselect_b64 s[8:9], -1, 0
	s_waitcnt vmcnt(6)
	s_mov_b32 s13, 0
	v_writelane_b32 v254, s7, 30
	s_and_b64 s[6:7], s[8:9], exec
	v_readlane_b32 s6, v254, 14
	v_readlane_b32 s7, v254, 15
	s_cselect_b32 s50, 0x500, s6
	v_readlane_b32 s6, v254, 49
	v_readlane_b32 s7, v254, 50
	v_writelane_b32 v254, s8, 25
	s_cselect_b32 s51, 0, 0
	s_and_b64 s[60:61], s[6:7], s[8:9]
	v_writelane_b32 v254, s9, 26
	s_cmp_lg_u32 s75, 1
	v_readlane_b32 s24, v254, 27
	v_readlane_b32 s25, v254, 28
	s_cselect_b64 s[6:7], -1, 0
	s_xor_b64 s[8:9], s[24:25], -1
	s_or_b64 s[62:63], s[8:9], s[6:7]
	s_cmp_eq_u32 s75, 2
	s_cselect_b64 s[6:7], -1, 0
	s_and_b64 s[54:55], s[24:25], s[6:7]
	s_and_b64 s[6:7], s[54:55], exec
	s_cselect_b32 s12, 0x4000, 0
	s_abs_i32 s89, s88
	v_cvt_f32_u32_e32 v0, s89
	s_sub_i32 s6, 0, s89
	v_lshl_or_b32 v159, s10, 7, v228
	s_mov_b32 s53, s75
	v_rcp_iflag_f32_e32 v0, v0
	v_or_b32_e32 v167, s10, v225
	s_bfe_i32 s52, s11, 0x1001c
	v_lshl_add_u64 v[152:153], s[64:65], 0, v[146:147]
	v_mul_f32_e32 v0, 0x4f7ffffe, v0
	v_cvt_u32_f32_e32 v0, v0
	v_lshl_add_u64 v[154:155], s[64:65], 0, v[144:145]
	v_add_u32_e32 v168, 0, v14
	s_mov_b32 s24, s13
	v_readfirstlane_b32 s7, v0
	s_mul_i32 s6, s6, s7
	s_mul_hi_u32 s6, s7, s6
	s_add_i32 s92, s7, s6
	s_barrier
	s_branch .LBB0_667

.LBB0_677:
	s_add_u32 s25, s20, 0x100
	s_addc_u32 s38, s21, 0
	s_add_u32 s30, s30, 0x80
	v_mov_b64_e32 v[0:1], 0
	v_mov_b64_e32 v[2:3], 0
	v_mov_b64_e32 v[4:5], 0
	v_mov_b64_e32 v[6:7], 0
	v_mov_b64_e32 v[8:9], 0
	v_mov_b64_e32 v[10:11], 0
	v_mov_b64_e32 v[12:13], 0
	v_mov_b64_e32 v[14:15], 0
	v_mov_b64_e32 v[16:17], 0
	v_mov_b64_e32 v[18:19], 0
	v_mov_b64_e32 v[20:21], 0
	v_mov_b64_e32 v[22:23], 0
	v_mov_b64_e32 v[24:25], 0
	v_mov_b64_e32 v[26:27], 0
	v_mov_b64_e32 v[28:29], 0
	v_mov_b64_e32 v[30:31], 0
	v_mov_b64_e32 v[32:33], 0
	v_mov_b64_e32 v[34:35], 0
	v_mov_b64_e32 v[36:37], 0
	v_mov_b64_e32 v[38:39], 0
	v_mov_b64_e32 v[40:41], 0
	v_mov_b64_e32 v[42:43], 0
	v_mov_b64_e32 v[44:45], 0
	v_mov_b64_e32 v[46:47], 0
	v_mov_b64_e32 v[48:49], 0
	v_mov_b64_e32 v[50:51], 0
	v_mov_b64_e32 v[52:53], 0
	v_mov_b64_e32 v[54:55], 0
	v_mov_b64_e32 v[56:57], 0
	v_mov_b64_e32 v[58:59], 0
	v_mov_b64_e32 v[60:61], 0
	v_mov_b64_e32 v[62:63], 0
	v_mov_b64_e32 v[64:65], 0
	v_mov_b64_e32 v[66:67], 0
	v_mov_b64_e32 v[68:69], 0
	v_mov_b64_e32 v[70:71], 0
	v_mov_b64_e32 v[72:73], 0
	v_mov_b64_e32 v[74:75], 0
	v_mov_b64_e32 v[76:77], 0
	v_mov_b64_e32 v[78:79], 0
	v_mov_b64_e32 v[84:85], 0
	v_mov_b64_e32 v[86:87], 0
	v_mov_b64_e32 v[88:89], 0
	v_mov_b64_e32 v[90:91], 0
	v_mov_b64_e32 v[92:93], 0
	v_mov_b64_e32 v[94:95], 0
	v_mov_b64_e32 v[96:97], 0
	v_mov_b64_e32 v[98:99], 0
	v_mov_b64_e32 v[100:101], 0
	v_mov_b64_e32 v[102:103], 0
	v_mov_b64_e32 v[104:105], 0
	v_mov_b64_e32 v[106:107], 0
	v_mov_b64_e32 v[108:109], 0
	v_mov_b64_e32 v[110:111], 0
	v_mov_b64_e32 v[116:117], 0
	v_mov_b64_e32 v[118:119], 0
	v_mov_b64_e32 v[120:121], 0
	v_mov_b64_e32 v[122:123], 0
	v_mov_b64_e32 v[124:125], 0
	v_mov_b64_e32 v[126:127], 0
	v_mov_b64_e32 v[128:129], 0
	v_mov_b64_e32 v[130:131], 0
	v_mov_b64_e32 v[132:133], 0
	v_mov_b64_e32 v[134:135], 0
	s_addc_u32 s31, s31, 0
	s_mov_b32 s20, 0
	s_nop 0
